# attention steps: the 16 K/V prefetch registers are zeroed only on the no-prefetch path (dead zeroing removed from every step)
# speedup vs baseline: 1.0043x; 1.0043x over previous
.LBB0_623:
	ds_read_b128 v[174:177], v212
	ds_read_b128 v[240:243], v212 offset:64
	ds_read_b128 v[248:251], v212 offset:128
	ds_read_b128 v[252:255], v212 offset:192
	s_add_i32 s0, s31, 1
	s_cmp_lt_i32 s0, s28
	s_cselect_b64 s[18:19], -1, 0
	s_cmp_ge_i32 s0, s28
	s_cselect_b64 s[16:17], -1, 0
	v_readfirstlane_b32 s2, v239
	v_readfirstlane_b32 s3, v247
	s_ashr_i32 s98, s2, 5
	v_lshl_add_u32 v239, s98, 2, v195
	ds_read_b32 v247, v239 offset:256
	ds_read_b32 v239, v239
	s_and_b64 vcc, exec, s[16:17]
	s_waitcnt vmcnt(0)
	s_cbranch_vccnz .Lz16_0
	s_mul_i32 s0, s3, 0x60000
	s_mul_hi_i32 s1, s3, 0x60000
	s_add_u32 s0, s12, s0
	s_addc_u32 s1, s13, s1
	s_lshl_b32 s8, s3, 6
	s_ashr_i32 s9, s8, 31
	v_lshl_add_u64 v[30:31], v[166:167], 1, s[0:1]
	v_lshl_add_u64 v[100:101], v[168:169], 1, s[0:1]
	s_lshl_b64 s[0:1], s[8:9], 1
	s_add_u32 s0, s14, s0
	s_addc_u32 s1, s15, s1
	global_load_dwordx4 v[104:107], v[30:31], off offset:2048
	global_load_dwordx4 v[108:111], v[100:101], off offset:2048
	v_lshl_add_u64 v[30:31], v[170:171], 1, s[0:1]
	v_lshl_add_u64 v[100:101], v[172:173], 1, s[0:1]
	global_load_dwordx4 v[112:115], v[30:31], off
	s_nop 0
	global_load_dwordx4 v[100:103], v[100:101], off
	s_branch .LBB0_625
.Lz16_0:
	v_mov_b32_e32 v100, 0
	v_mov_b32_e32 v101, 0
	v_mov_b32_e32 v102, 0
	v_mov_b32_e32 v103, 0
	v_mov_b32_e32 v104, 0
	v_mov_b32_e32 v105, 0
	v_mov_b32_e32 v106, 0
	v_mov_b32_e32 v107, 0
	v_mov_b32_e32 v108, 0
	v_mov_b32_e32 v109, 0
	v_mov_b32_e32 v110, 0
	v_mov_b32_e32 v111, 0
	v_mov_b32_e32 v112, 0
	v_mov_b32_e32 v113, 0
	v_mov_b32_e32 v114, 0
	v_mov_b32_e32 v115, 0

.LBB0_650:
	s_andn2_b64 vcc, exec, s[0:1]
	s_cbranch_vccnz .LBB0_622
	ds_read_b128 v[174:177], v214 offset:11328
	ds_read_b128 v[240:243], v214 offset:11392
	ds_read_b128 v[248:251], v214 offset:11456
	ds_read_b128 v[252:255], v214 offset:11520
	s_add_i32 s31, s31, 2
	s_cmp_lt_i32 s31, s28
	s_waitcnt vmcnt(0)
	s_cselect_b64 s[16:17], -1, 0
	v_readfirstlane_b32 s2, v239
	v_readfirstlane_b32 s3, v247
	s_ashr_i32 s98, s2, 5
	v_lshl_add_u32 v239, s98, 2, v195
	ds_read_b32 v247, v239 offset:256
	ds_read_b32 v239, v239
	s_cmp_ge_i32 s31, s28
	s_cbranch_scc1 .Lz16_1
	s_mul_i32 s0, s3, 0x60000
	s_mul_hi_i32 s1, s3, 0x60000
	s_add_u32 s0, s12, s0
	s_addc_u32 s1, s13, s1
	s_lshl_b32 s8, s3, 6
	s_ashr_i32 s9, s8, 31
	v_lshl_add_u64 v[30:31], v[166:167], 1, s[0:1]
	v_lshl_add_u64 v[100:101], v[168:169], 1, s[0:1]
	s_lshl_b64 s[0:1], s[8:9], 1
	s_add_u32 s0, s14, s0
	s_addc_u32 s1, s15, s1
	global_load_dwordx4 v[104:107], v[30:31], off offset:2048
	global_load_dwordx4 v[108:111], v[100:101], off offset:2048
	v_lshl_add_u64 v[30:31], v[170:171], 1, s[0:1]
	v_lshl_add_u64 v[100:101], v[172:173], 1, s[0:1]
	global_load_dwordx4 v[112:115], v[30:31], off
	s_nop 0
	global_load_dwordx4 v[100:103], v[100:101], off
	s_branch .LBB0_653

.LBB0_691:
	s_add_i32 s2, s17, -8
	v_mov_b32_e32 v30, s2
	ds_read_b32 v30, v30
	s_cmp_lt_i32 s18, s16
	s_cselect_b64 s[14:15], -1, 0
	s_cmp_ge_i32 s18, s16
	s_cselect_b64 s[12:13], -1, 0
	s_waitcnt lgkmcnt(0)
	v_readfirstlane_b32 s2, v30
	s_and_b64 vcc, exec, s[12:13]
	s_waitcnt vmcnt(0)
	s_cbranch_vccnz .Lz16_2
	s_add_i32 s3, s17, -4
	v_mov_b32_e32 v30, s3
	ds_read_b32 v30, v30
	s_waitcnt lgkmcnt(0)
	v_readfirstlane_b32 s3, v30
	s_mul_i32 s8, s3, 0x60000
	s_mul_hi_i32 s7, s3, 0x60000
	s_add_u32 s8, s0, s8
	s_addc_u32 s9, s1, s7
	s_lshl_b32 s20, s3, 6
	s_ashr_i32 s21, s20, 31
	v_lshl_add_u64 v[30:31], v[158:159], 1, s[8:9]
	v_lshl_add_u64 v[100:101], v[162:163], 1, s[8:9]
	s_lshl_b64 s[8:9], s[20:21], 1
	s_add_u32 s8, s10, s8
	s_addc_u32 s9, s11, s9
	global_load_dwordx4 v[104:107], v[30:31], off
	global_load_dwordx4 v[108:111], v[100:101], off
	v_lshl_add_u64 v[30:31], v[164:165], 1, s[8:9]
	v_lshl_add_u64 v[100:101], v[166:167], 1, s[8:9]
	global_load_dwordx4 v[112:115], v[30:31], off
	s_nop 0
	global_load_dwordx4 v[100:103], v[100:101], off
	s_branch .LBB0_693

.LBB0_701:
	v_add_f32_e32 v184, v123, v124
	v_add_f32_e32 v185, v135, v136
	v_fmac_f32_e32 v184, v180, v116
	s_andn2_b64 vcc, exec, s[2:3]
	v_fmac_f32_e32 v185, v181, v30
	s_cbranch_vccnz .LBB0_710
	s_add_i32 s2, s17, -4
	v_mov_b32_e32 v29, s2
	ds_read_b32 v29, v29
	s_add_i32 s18, s18, 2
	s_cmp_le_i32 s18, s16
	s_waitcnt vmcnt(0)
	s_cselect_b64 s[12:13], -1, 0
	s_waitcnt lgkmcnt(0)
	v_readfirstlane_b32 s2, v29
	s_cmp_gt_i32 s18, s16
	s_cbranch_scc1 .Lz16_3
	v_mov_b32_e32 v29, s17
	ds_read_b32 v29, v29
	s_waitcnt lgkmcnt(0)
	v_readfirstlane_b32 s3, v29
	s_mul_i32 s8, s3, 0x60000
	s_mul_hi_i32 s7, s3, 0x60000
	s_add_u32 s8, s0, s8
	s_addc_u32 s9, s1, s7
	s_lshl_b32 s14, s3, 6
	s_ashr_i32 s15, s14, 31
	v_lshl_add_u64 v[100:101], v[158:159], 1, s[8:9]
	v_lshl_add_u64 v[102:103], v[162:163], 1, s[8:9]
	s_lshl_b64 s[8:9], s[14:15], 1
	s_add_u32 s8, s10, s8
	s_addc_u32 s9, s11, s9
	global_load_dwordx4 v[104:107], v[100:101], off
	global_load_dwordx4 v[108:111], v[102:103], off
	v_lshl_add_u64 v[100:101], v[164:165], 1, s[8:9]
	v_lshl_add_u64 v[102:103], v[166:167], 1, s[8:9]
	global_load_dwordx4 v[112:115], v[100:101], off
	s_nop 0
	global_load_dwordx4 v[100:103], v[102:103], off
	s_branch .LBB0_704
